# v7 + prep_phase: the 24 conditional conv-input loads of the first token of each iteration are issued back to back (was: vmcnt(0) after each)
# speedup vs baseline: 1.0071x; 1.0071x over previous
.LBB0_1025:
	v_ashrrev_i32_e32 v43, 31, v42
	v_lshlrev_b64 v[58:59], 12, v[42:43]
	v_lshl_add_u64 v[64:65], s[82:83], 0, v[58:59]
	v_lshlrev_b32_e32 v128, 1, v46
	s_mov_b32 s16, s19
	v_lshl_add_u64 v[92:93], v[64:65], 0, v[128:129]
	v_lshlrev_b32_e32 v62, 1, v52
	v_mov_b32_e32 v63, v129
	v_lshlrev_b32_e32 v60, 1, v4
	v_mov_b32_e32 v61, v129
	v_lshlrev_b32_e32 v58, 1, v38
	v_mov_b32_e32 v59, v129
	v_lshlrev_b32_e32 v94, 1, v44
	v_mov_b32_e32 v95, v129
	v_lshl_add_u64 v[90:91], v[64:65], 0, v[62:63]
	v_lshl_add_u64 v[84:85], v[64:65], 0, v[60:61]
	v_lshl_add_u64 v[80:81], v[64:65], 0, v[58:59]
	v_lshl_add_u64 v[64:65], v[64:65], 0, v[94:95]
	global_load_ushort v231, v[92:93], off offset:512
	global_load_ushort v232, v[92:93], off offset:544
	global_load_ushort v229, v[90:91], off offset:2336
	global_load_ushort v230, v[90:91], off offset:2352
	global_load_dwordx2 v[88:89], v[84:85], off offset:1568
	global_load_dword v228, v[80:81], off offset:2080
	global_load_ushort v207, v[64:65], off offset:1536
	s_mov_b32 s10, 0x8000
	v_cmp_gt_i32_e32 vcc, s10, v42
	v_cmp_lt_i32_e64 s[10:11], s42, v42
	v_mov_b64_e32 v[64:65], s[50:51]
	s_movk_i32 s12, 0x600
	v_cndmask_b32_e64 v59, v192, v193, s[10:11]
	v_and_b32_e32 v61, v59, v42
	v_cmp_ne_u32_e64 s[10:11], 0, v61
	v_mad_i64_i32 v[64:65], s[12:13], v42, s12, v[64:65]
	v_mov_b32_e32 v86, 0
	s_and_saveexec_b64 s[12:13], s[10:11]
	s_cbranch_execz .LBB0_1027
	v_mov_b32_e32 v39, v129
	v_lshl_add_u64 v[66:67], v[64:65], 0, v[38:39]
	global_load_ushort v86, v[66:67], off offset:-1536
.LBB0_1027:
	s_or_b64 exec, exec, s[12:13]
	v_mov_b32_e32 v39, v129
	v_lshl_add_u64 v[64:65], v[64:65], 0, v[38:39]
	global_load_ushort v227, v[64:65], off
	v_cmp_ne_u32_e64 s[12:13], v61, v59
	v_mov_b32_e32 v82, 0
	v_mov_b32_e32 v87, 0
	s_and_saveexec_b64 s[14:15], s[12:13]
	s_cbranch_execz .LBB0_1029
	global_load_ushort v87, v[64:65], off offset:1536
.LBB0_1029:
	s_or_b64 exec, exec, s[14:15]
	s_and_saveexec_b64 s[14:15], s[10:11]
	s_cbranch_execz .LBB0_1031
	global_load_ushort v82, v[64:65], off offset:-1408
.LBB0_1031:
	s_or_b64 exec, exec, s[14:15]
	global_load_ushort v226, v[64:65], off offset:128
	v_mov_b32_e32 v78, 0
	v_mov_b32_e32 v83, 0
	s_and_saveexec_b64 s[14:15], s[12:13]
	s_cbranch_execz .LBB0_1033
	global_load_ushort v83, v[64:65], off offset:1664
.LBB0_1033:
	s_or_b64 exec, exec, s[14:15]
	s_and_saveexec_b64 s[14:15], s[10:11]
	s_cbranch_execz .LBB0_1035
	global_load_ushort v78, v[64:65], off offset:-1280
.LBB0_1035:
	s_or_b64 exec, exec, s[14:15]
	global_load_ushort v225, v[64:65], off offset:256
	v_mov_b32_e32 v76, 0
	v_mov_b32_e32 v79, 0
	s_and_saveexec_b64 s[14:15], s[12:13]
	s_cbranch_execz .LBB0_1037
	global_load_ushort v79, v[64:65], off offset:1792
.LBB0_1037:
	s_or_b64 exec, exec, s[14:15]
	s_and_saveexec_b64 s[14:15], s[10:11]
	s_cbranch_execz .LBB0_1039
	global_load_ushort v76, v[64:65], off offset:-1152
.LBB0_1039:
	s_or_b64 exec, exec, s[14:15]
	global_load_ushort v224, v[64:65], off offset:384
	v_mov_b32_e32 v74, 0
	v_mov_b32_e32 v77, 0
	s_and_saveexec_b64 s[14:15], s[12:13]
	s_cbranch_execz .LBB0_1041
	global_load_ushort v77, v[64:65], off offset:1920
.LBB0_1041:
	s_or_b64 exec, exec, s[14:15]
	s_and_saveexec_b64 s[14:15], s[10:11]
	s_cbranch_execz .LBB0_1043
	global_load_ushort v74, v[64:65], off offset:-1024
.LBB0_1043:
	s_or_b64 exec, exec, s[14:15]
	global_load_ushort v223, v[64:65], off offset:512
	v_mov_b32_e32 v72, 0
	v_mov_b32_e32 v75, 0
	s_and_saveexec_b64 s[14:15], s[12:13]
	s_cbranch_execz .LBB0_1045
	global_load_ushort v75, v[64:65], off offset:2048
.LBB0_1045:
	s_or_b64 exec, exec, s[14:15]
	s_and_saveexec_b64 s[14:15], s[10:11]
	s_cbranch_execz .LBB0_1047
	global_load_ushort v72, v[64:65], off offset:-896
.LBB0_1047:
	s_or_b64 exec, exec, s[14:15]
	global_load_ushort v222, v[64:65], off offset:640
	v_mov_b32_e32 v70, 0
	v_mov_b32_e32 v73, 0
	s_and_saveexec_b64 s[14:15], s[12:13]
	s_cbranch_execz .LBB0_1049
	global_load_ushort v73, v[64:65], off offset:2176
.LBB0_1049:
	s_or_b64 exec, exec, s[14:15]
	s_and_saveexec_b64 s[14:15], s[10:11]
	s_cbranch_execz .LBB0_1051
	global_load_ushort v70, v[64:65], off offset:-768
.LBB0_1051:
	s_or_b64 exec, exec, s[14:15]
	global_load_ushort v221, v[64:65], off offset:768
	v_mov_b32_e32 v68, 0
	v_mov_b32_e32 v71, 0
	s_and_saveexec_b64 s[14:15], s[12:13]
	s_cbranch_execz .LBB0_1053
	global_load_ushort v71, v[64:65], off offset:2304
.LBB0_1053:
	s_or_b64 exec, exec, s[14:15]
	s_and_saveexec_b64 s[14:15], s[10:11]
	s_cbranch_execz .LBB0_1055
	global_load_ushort v68, v[64:65], off offset:-640
.LBB0_1055:
	s_or_b64 exec, exec, s[14:15]
	global_load_ushort v217, v[64:65], off offset:896
	v_mov_b32_e32 v208, 0
	v_mov_b32_e32 v69, 0
	s_and_saveexec_b64 s[14:15], s[12:13]
	s_cbranch_execz .LBB0_1057
	global_load_ushort v69, v[64:65], off offset:2432
.LBB0_1057:
	s_or_b64 exec, exec, s[14:15]
	s_and_saveexec_b64 s[14:15], s[10:11]
	s_cbranch_execz .LBB0_1059
	global_load_ushort v208, v[64:65], off offset:-512
.LBB0_1059:
	s_or_b64 exec, exec, s[14:15]
	global_load_ushort v212, v[64:65], off offset:1024
	v_mov_b32_e32 v209, 0
	v_mov_b32_e32 v211, 0
	s_and_saveexec_b64 s[14:15], s[12:13]
	s_cbranch_execz .LBB0_1061
	global_load_ushort v211, v[64:65], off offset:2560
.LBB0_1061:
	s_or_b64 exec, exec, s[14:15]
	s_and_saveexec_b64 s[14:15], s[10:11]
	s_cbranch_execz .LBB0_1063
	global_load_ushort v209, v[64:65], off offset:-384
.LBB0_1063:
	s_or_b64 exec, exec, s[14:15]
	global_load_ushort v215, v[64:65], off offset:1152
	v_mov_b32_e32 v210, 0
	v_mov_b32_e32 v214, 0
	s_and_saveexec_b64 s[14:15], s[12:13]
	s_cbranch_execz .LBB0_1065
	global_load_ushort v214, v[64:65], off offset:2688
.LBB0_1065:
	s_or_b64 exec, exec, s[14:15]
	s_and_saveexec_b64 s[14:15], s[10:11]
	s_cbranch_execz .LBB0_1067
	global_load_ushort v210, v[64:65], off offset:-256
.LBB0_1067:
	s_or_b64 exec, exec, s[14:15]
	global_load_ushort v218, v[64:65], off offset:1280
	v_mov_b32_e32 v213, 0
	v_mov_b32_e32 v216, 0
	s_and_saveexec_b64 s[14:15], s[12:13]
	s_cbranch_execz .LBB0_1069
	global_load_ushort v216, v[64:65], off offset:2816
.LBB0_1069:
	s_or_b64 exec, exec, s[14:15]
	s_and_saveexec_b64 s[14:15], s[10:11]
	s_cbranch_execz .LBB0_1071
	global_load_ushort v213, v[64:65], off offset:-128
.LBB0_1071:
	s_or_b64 exec, exec, s[14:15]
	global_load_ushort v220, v[64:65], off offset:1408
	v_mov_b32_e32 v219, 0
	s_and_saveexec_b64 s[10:11], s[12:13]
	s_cbranch_execz .LBB0_1073
	global_load_ushort v219, v[64:65], off offset:2944
.LBB0_1073:
	s_or_b64 exec, exec, s[10:11]
	s_waitcnt vmcnt(0)
	v_lshlrev_b32_e32 v86, 16, v86
	v_lshlrev_b32_e32 v87, 16, v87
	v_lshlrev_b32_e32 v82, 16, v82
	v_lshlrev_b32_e32 v83, 16, v83
	v_lshlrev_b32_e32 v78, 16, v78
	v_lshlrev_b32_e32 v79, 16, v79
	v_lshlrev_b32_e32 v76, 16, v76
	v_lshlrev_b32_e32 v77, 16, v77
	v_lshlrev_b32_e32 v74, 16, v74
	v_lshlrev_b32_e32 v75, 16, v75
	v_lshlrev_b32_e32 v72, 16, v72
	v_lshlrev_b32_e32 v73, 16, v73
	v_lshlrev_b32_e32 v70, 16, v70
	v_lshlrev_b32_e32 v71, 16, v71
	v_lshlrev_b32_e32 v68, 16, v68
	v_lshlrev_b32_e32 v69, 16, v69
	v_lshlrev_b32_e32 v208, 16, v208
	v_lshlrev_b32_e32 v211, 16, v211
	v_lshlrev_b32_e32 v209, 16, v209
	v_lshlrev_b32_e32 v214, 16, v214
	v_lshlrev_b32_e32 v210, 16, v210
	v_lshlrev_b32_e32 v216, 16, v216
	v_lshlrev_b32_e32 v213, 16, v213
	v_lshlrev_b32_e32 v219, 16, v219
	v_lshl_add_u32 v66, s16, 2, v42
	s_mov_b32 s10, 0x8800
	v_cmp_gt_i32_e64 s[12:13], s10, v66
	v_ashrrev_i32_e32 v67, 31, v66
	s_and_saveexec_b64 s[16:17], s[12:13]
	s_cbranch_execz .LBB0_1123
	v_lshlrev_b64 v[56:57], 12, v[66:67]
	v_lshl_add_u64 v[64:65], s[82:83], 0, v[56:57]
	v_lshl_add_u64 v[56:57], v[64:65], 0, v[128:129]
	v_mov_b32_e32 v63, v129
	global_load_ushort v114, v[56:57], off offset:512
	global_load_ushort v115, v[56:57], off offset:544
	v_lshl_add_u64 v[56:57], v[64:65], 0, v[62:63]
	v_mov_b32_e32 v61, v129
	v_mov_b32_e32 v59, v129
	v_mov_b32_e32 v95, v129
	global_load_ushort v63, v[56:57], off offset:2336
	global_load_ushort v96, v[56:57], off offset:2352
	v_lshl_add_u64 v[56:57], v[64:65], 0, v[60:61]
	v_lshl_add_u64 v[120:121], v[64:65], 0, v[58:59]
	v_lshl_add_u64 v[64:65], v[64:65], 0, v[94:95]
	global_load_dwordx2 v[56:57], v[56:57], off offset:1568
	v_cmp_lt_i32_e64 s[10:11], s42, v66
	global_load_dword v118, v[120:121], off offset:2080
	s_movk_i32 s14, 0x600
	global_load_ushort v120, v[64:65], off offset:1536
	v_cndmask_b32_e64 v61, v192, v193, s[10:11]
	v_and_b32_e32 v95, v61, v66
	v_mov_b64_e32 v[64:65], s[50:51]
	v_cmp_ne_u32_e64 s[10:11], 0, v95
	v_mad_i64_i32 v[64:65], s[14:15], v66, s14, v[64:65]
	v_mov_b32_e32 v59, 0
	v_mov_b32_e32 v121, 0
	s_and_saveexec_b64 s[14:15], s[10:11]
	s_cbranch_execz .LBB0_1076
	v_mov_b32_e32 v39, v129
	v_lshl_add_u64 v[148:149], v[64:65], 0, v[38:39]
	global_load_ushort v121, v[148:149], off offset:-1536
